# pass3: the unit's 28 operand loads issued with the 8 staging loads (one memory round trip per unit instead of two)
# baseline (speedup 1.0000x reference)
; #define LAS __attribute__((address_space(3)))
; __device__ __forceinline__ void hgrn_pass3_unit(Frame& F, const float* onw, int pu) {
;     const int unit0 = 2 * pu, fr = F.lane & 15, fq = F.lane >> 4;
;     const bf16* UT = (const bf16*)F.out + (size_t)unit0 * 16384; const float* LF = (const float*)(F.ws + WS_LF); bf16* QO = (bf16*)(F.ws + WS_QO); const bf16* GH = (const bf16*)(F.ws + WS_GH);
; #pragma unroll
;     for (int i = 0; i < 8; ++i) { const int p = F.tid + 512 * i, cc = p >> 11, q = p & 2047, v = q >> 4, c8 = q & 15;
;         *(LAS v4u*)(F.lds + cc * 34816 + v * 272 + c8 * 16) = *(const v4u*)(UT + (size_t)cc * 16384 + v * 128 + c8 * 8); }
;     __syncthreads();
;     const int cc = F.wave >> 2, tt = F.wave & 3, unit = unit0 + cc, bh = unit >> 7, c = unit & 127, b = bh >> 2, h = bh & 3;
;     const size_t row = (size_t)b * SEQ + c * 64 + 16 * tt + fr;
;     bf16x8_t yq[4];
; #pragma unroll
;     for (int kk = 0; kk < 4; ++kk) yq[kk] = *(const bf16x8_t*)(QO + row * DM + h * 128 + 8 * fq + 32 * kk);
;     ...
;     for (int vt = 0; vt < 8; ++vt) { const int v0 = 16 * vt + 4 * fq; const f32x4 w4 = *(const f32x4*)(onw + v0); const v2u gt = *(const v2u*)(GH + row * 512 + h * 128 + v0);
.LBB0_696:
	s_ashr_i32 s13, s12, 31
	s_lshl_b64 s[14:15], s[12:13], 15
	s_add_u32 s14, s4, s14
	s_addc_u32 s15, s5, s15
	v_lshl_add_u64 v[110:111], s[14:15], 0, v[44:45]
	v_lshl_add_u64 v[110:111], v[110:111], 0, v[192:193]
	v_mov_b32_e32 v65, v193
	v_lshl_add_u64 v[110:111], v[110:111], 0, v[64:65]
	global_load_dwordx4 v[110:113], v[110:111], off
	v_mov_b32_e32 v67, v193
	v_mov_b32_e32 v69, v193
	v_mov_b32_e32 v71, v193
	v_mov_b32_e32 v73, v193
	v_mov_b32_e32 v75, v193
	v_mov_b32_e32 v77, v193
	s_add_i32 s2, s16, s12
	s_and_b32 s13, s17, 0x1fc0
	v_mov_b32_e32 v79, v193
	v_mov_b32_e32 v81, v193
	s_add_i32 s0, s0, s1
	s_add_i32 s17, s17, s18
	s_add_i32 s12, s12, s19
	v_lshl_add_u64 v[114:115], s[14:15], 0, v[46:47]
	v_lshl_add_u64 v[114:115], v[114:115], 0, v[66:67]
	v_lshl_add_u64 v[114:115], v[114:115], 0, v[64:65]
	global_load_dwordx4 v[114:117], v[114:115], off
	v_lshl_add_u64 v[118:119], s[14:15], 0, v[48:49]
	v_lshl_add_u64 v[118:119], v[118:119], 0, v[68:69]
	v_lshl_add_u64 v[118:119], v[118:119], 0, v[64:65]
	global_load_dwordx4 v[118:121], v[118:119], off
	v_lshl_add_u64 v[122:123], s[14:15], 0, v[50:51]
	v_lshl_add_u64 v[122:123], v[122:123], 0, v[70:71]
	v_lshl_add_u64 v[122:123], v[122:123], 0, v[64:65]
	global_load_dwordx4 v[122:125], v[122:123], off
	v_lshl_add_u64 v[126:127], s[14:15], 0, v[52:53]
	v_lshl_add_u64 v[126:127], v[126:127], 0, v[192:193]
	v_lshl_add_u64 v[126:127], v[126:127], 0, v[64:65]
	global_load_dwordx4 v[126:129], v[126:127], off
	v_lshl_add_u64 v[130:131], s[14:15], 0, v[54:55]
	v_lshl_add_u64 v[130:131], v[130:131], 0, v[72:73]
	v_lshl_add_u64 v[130:131], v[130:131], 0, v[64:65]
	global_load_dwordx4 v[130:133], v[130:131], off
	v_lshl_add_u64 v[134:135], s[14:15], 0, v[56:57]
	v_lshl_add_u64 v[134:135], v[134:135], 0, v[74:75]
	v_lshl_add_u64 v[134:135], v[134:135], 0, v[64:65]
	global_load_dwordx4 v[134:137], v[134:135], off
	v_lshl_add_u64 v[138:139], s[14:15], 0, v[58:59]
	v_lshl_add_u64 v[138:139], v[138:139], 0, v[76:77]
	v_lshl_add_u64 v[138:139], v[138:139], 0, v[64:65]
	global_load_dwordx4 v[138:141], v[138:139], off
	s_ashr_i32 s14, s2, 9
	s_ashr_i32 s15, s14, 31
	s_lshl_b64 s[14:15], s[14:15], 13
	s_or_b32 s13, s14, s13
	s_and_b32 s2, s2, 0x180
	s_lshl_b32 s68, s2, 1
	s_cmpk_gt_i32 s0, 0x1ff
	v_mov_b32_e32 v1, s15
	v_or_b32_e32 v0, s13, v60
	v_lshlrev_b64 v[2:3], 11, v[0:1]
	v_lshlrev_b64 v[84:85], 10, v[0:1]
	v_lshl_add_u64 v[2:3], s[6:7], 0, v[2:3]
	v_lshl_add_u64 v[0:1], s[8:9], 0, v[84:85]
	v_lshl_add_u64 v[82:83], v[2:3], 0, s[68:69]
	v_lshl_add_u64 v[0:1], v[0:1], 0, s[68:69]
	v_lshl_add_u64 v[2:3], v[82:83], 0, v[78:79]
	v_lshl_add_u64 v[86:87], v[0:1], 0, v[80:81]
	global_load_dwordx4 v[40:43], v[2:3], off
	global_load_dwordx4 v[36:39], v[2:3], off offset:64
	global_load_dwordx4 v[32:35], v[2:3], off offset:128
	global_load_dwordx4 v[12:15], v[2:3], off offset:192
	global_load_dwordx2 v[144:145], v[86:87], off
	global_load_dwordx2 v[146:147], v[86:87], off offset:32
	global_load_dwordx2 v[148:149], v[86:87], off offset:64
	global_load_dwordx2 v[150:151], v[86:87], off offset:96
	global_load_dwordx2 v[152:153], v[86:87], off offset:128
	global_load_dwordx2 v[154:155], v[86:87], off offset:160
	global_load_dwordx2 v[156:157], v[86:87], off offset:192
	global_load_dwordx2 v[158:159], v[86:87], off offset:224
	v_lshl_add_u64 v[142:143], s[10:11], 0, v[84:85]
	v_lshl_add_u64 v[142:143], v[142:143], 0, s[68:69]
	v_lshl_add_u64 v[142:143], v[142:143], 0, v[80:81]
	global_load_dwordx4 v[160:163], v[62:63], off
	global_load_dwordx4 v[166:169], v[62:63], off offset:64
	global_load_dwordx4 v[172:175], v[62:63], off offset:128
	global_load_dwordx4 v[178:181], v[62:63], off offset:192
	global_load_dwordx4 v[184:187], v[62:63], off offset:256
	global_load_dwordx4 v[204:207], v[62:63], off offset:320
	global_load_dwordx4 v[208:211], v[62:63], off offset:384
	global_load_dwordx4 v[220:223], v[62:63], off offset:448
	global_load_dwordx2 v[164:165], v[142:143], off
	global_load_dwordx2 v[170:171], v[142:143], off offset:32
	global_load_dwordx2 v[176:177], v[142:143], off offset:64
	global_load_dwordx2 v[182:183], v[142:143], off offset:96
	global_load_dwordx2 v[188:189], v[142:143], off offset:128
	global_load_dwordx2 v[190:191], v[142:143], off offset:160
	global_load_dwordx2 v[218:219], v[142:143], off offset:192
	global_load_dwordx2 v[224:225], v[142:143], off offset:224
	s_waitcnt vmcnt(35)
	ds_write_b128 v93, v[110:113]
	s_waitcnt vmcnt(34)
	ds_write_b128 v94, v[114:117]
	s_waitcnt vmcnt(33)
	ds_write_b128 v95, v[118:121]
	s_waitcnt vmcnt(32)
	ds_write_b128 v96, v[122:125]
	s_waitcnt vmcnt(31)
	ds_write_b128 v97, v[126:129]
	s_waitcnt vmcnt(30)
	ds_write_b128 v98, v[130:133]
	s_waitcnt vmcnt(29)
	ds_write_b128 v99, v[134:137]
	s_waitcnt vmcnt(28)
	ds_write_b128 v100, v[138:141]
	s_waitcnt lgkmcnt(0)
	s_barrier
; #define LAS __attribute__((address_space(3)))
; __device__ __forceinline__ float bflo(unsigned w) { return __uint_as_float(w << 16); }
; __device__ __forceinline__ float bfhi(unsigned w) { return __uint_as_float(w & 0xffff0000u); }
; __device__ __forceinline__ f32x4 mma16(bf16x8_t x, bf16x8_t y, f32x4 c) { return __builtin_amdgcn_mfma_f32_16x16x32_bf16(x, y, c, 0, 0, 0); }
; __device__ __forceinline__ void hgrn_pass3_unit(Frame& F, const float* onw, int pu) {
;     ...
;     f32x4 o[8]; float ss = 0.f;
; #pragma unroll
;     for (int vt = 0; vt < 8; ++vt) { const v2u oi = *(const v2u*)((const bf16*)F.out + (size_t)16 * 1024 * 1024 + row * 512 + h * 128 + 16 * vt + 4 * fq); f32x4 a; a[0] = bflo(oi.x); a[1] = bfhi(oi.x); a[2] = bflo(oi.y); a[3] = bfhi(oi.y);
; #pragma unroll
;         for (int kk = 0; kk < 4; ++kk) a = mma16(*(const LAS bf16x8_t*)(F.lds + cc * 34816 + (16 * vt + fr) * 272 + (8 * fq + 32 * kk) * 2), yq[kk], a);
;         o[vt] = a; ss += (a[0] * a[0] + a[1] * a[1]) + (a[2] * a[2] + a[3] * a[3]); }
	s_nop 0
	s_nop 0
	s_nop 0
	s_nop 0
	ds_read_b128 v[4:7], v101
	ds_read_b128 v[102:105], v101 offset:26112
	s_waitcnt vmcnt(23)
	ds_read_b128 v[106:109], v101 offset:30464
	s_waitcnt lgkmcnt(0)
	v_lshlrev_b32_e32 v0, 16, v144
	v_and_b32_e32 v1, 0xffff0000, v144
	v_lshlrev_b32_e32 v2, 16, v145
	v_and_b32_e32 v3, 0xffff0000, v145
	s_nop 1
	v_mfma_f32_16x16x32_bf16 v[0:3], v[4:7], v[40:43], v[0:3]
	ds_read_b128 v[4:7], v101 offset:64
	s_waitcnt lgkmcnt(0)
	v_mfma_f32_16x16x32_bf16 v[0:3], v[4:7], v[36:39], v[0:3]
	ds_read_b128 v[4:7], v101 offset:128
	s_waitcnt lgkmcnt(0)
	v_mfma_f32_16x16x32_bf16 v[0:3], v[4:7], v[32:35], v[0:3]
	ds_read_b128 v[4:7], v101 offset:192
	s_waitcnt lgkmcnt(0)
	v_mfma_f32_16x16x32_bf16 v[28:31], v[4:7], v[12:15], v[0:3]
	s_nop 4
	s_waitcnt vmcnt(22)
	ds_read_b128 v[4:7], v101 offset:4352
	s_waitcnt lgkmcnt(0)
	v_lshlrev_b32_e32 v0, 16, v146
	v_and_b32_e32 v1, 0xffff0000, v146
	v_lshlrev_b32_e32 v2, 16, v147
	v_and_b32_e32 v3, 0xffff0000, v147
	s_nop 1
	v_mfma_f32_16x16x32_bf16 v[0:3], v[4:7], v[40:43], v[0:3]
	ds_read_b128 v[4:7], v101 offset:4416
	s_waitcnt lgkmcnt(0)
	v_mfma_f32_16x16x32_bf16 v[0:3], v[4:7], v[36:39], v[0:3]
	ds_read_b128 v[4:7], v101 offset:4480
	s_waitcnt lgkmcnt(0)
	v_mfma_f32_16x16x32_bf16 v[0:3], v[4:7], v[32:35], v[0:3]
	ds_read_b128 v[4:7], v101 offset:4544
	s_waitcnt lgkmcnt(0)
	v_mfma_f32_16x16x32_bf16 v[24:27], v[4:7], v[12:15], v[0:3]
	s_nop 4
	v_mov_b32_e32 v2, v29
	v_mov_b32_e32 v0, v28
	v_mov_b32_e32 v4, v31
	v_mov_b32_e32 v3, v25
	v_mov_b32_e32 v1, v24
	v_pk_mul_f32 v[2:3], v[2:3], v[2:3]
	v_mov_b32_e32 v5, v27
	v_pk_fma_f32 v[0:1], v[0:1], v[0:1], v[2:3]
	v_mov_b32_e32 v2, v30
	v_mov_b32_e32 v3, v26
	v_pk_mul_f32 v[4:5], v[4:5], v[4:5]
	s_nop 0
	v_pk_fma_f32 v[2:3], v[2:3], v[2:3], v[4:5]
	ds_read_b128 v[4:7], v101 offset:8704
	v_pk_add_f32 v[88:89], v[0:1], v[2:3]
	s_waitcnt vmcnt(21)
	s_waitcnt lgkmcnt(0)
	v_lshlrev_b32_e32 v0, 16, v148
	v_and_b32_e32 v1, 0xffff0000, v148
	v_lshlrev_b32_e32 v2, 16, v149
	v_and_b32_e32 v3, 0xffff0000, v149
	s_nop 1
	v_mfma_f32_16x16x32_bf16 v[0:3], v[4:7], v[40:43], v[0:3]
	ds_read_b128 v[4:7], v101 offset:8768
	s_waitcnt lgkmcnt(0)
	v_mfma_f32_16x16x32_bf16 v[0:3], v[4:7], v[36:39], v[0:3]
	ds_read_b128 v[4:7], v101 offset:8832
	s_waitcnt lgkmcnt(0)
	v_mfma_f32_16x16x32_bf16 v[0:3], v[4:7], v[32:35], v[0:3]
	ds_read_b128 v[4:7], v101 offset:8896
	s_waitcnt lgkmcnt(0)
	v_mfma_f32_16x16x32_bf16 v[20:23], v[4:7], v[12:15], v[0:3]
	s_nop 7
	v_pk_mul_f32 v[0:1], v[22:23], v[22:23]
	v_pk_mul_f32 v[2:3], v[20:21], v[20:21]
	s_nop 0
	v_pk_mov_b32 v[4:5], v[2:3], v[0:1] op_sel:[1,0]
	v_mov_b32_e32 v3, v1
	v_pk_add_f32 v[90:91], v[4:5], v[2:3]
	s_waitcnt vmcnt(20)
	ds_read_b128 v[4:7], v101 offset:13056
	s_waitcnt lgkmcnt(0)
	v_lshlrev_b32_e32 v0, 16, v150
	v_and_b32_e32 v1, 0xffff0000, v150
	v_lshlrev_b32_e32 v2, 16, v151
	v_and_b32_e32 v3, 0xffff0000, v151
	s_nop 1
	v_mfma_f32_16x16x32_bf16 v[0:3], v[4:7], v[40:43], v[0:3]
	ds_read_b128 v[4:7], v101 offset:13120
	s_waitcnt lgkmcnt(0)
	v_mfma_f32_16x16x32_bf16 v[0:3], v[4:7], v[36:39], v[0:3]
	ds_read_b128 v[4:7], v101 offset:13184
	s_waitcnt lgkmcnt(0)
	v_mfma_f32_16x16x32_bf16 v[0:3], v[4:7], v[32:35], v[0:3]
	ds_read_b128 v[4:7], v101 offset:13248
	s_waitcnt lgkmcnt(0)
	v_mfma_f32_16x16x32_bf16 v[16:19], v[4:7], v[12:15], v[0:3]
	s_nop 4
	s_waitcnt vmcnt(19)
	ds_read_b128 v[4:7], v101 offset:17408
	s_waitcnt lgkmcnt(0)
	v_lshlrev_b32_e32 v0, 16, v152
	v_and_b32_e32 v1, 0xffff0000, v152
	v_lshlrev_b32_e32 v2, 16, v153
	v_and_b32_e32 v3, 0xffff0000, v153
	s_nop 1
	v_mfma_f32_16x16x32_bf16 v[0:3], v[4:7], v[40:43], v[0:3]
	ds_read_b128 v[4:7], v101 offset:17472
	s_waitcnt lgkmcnt(0)
	v_mfma_f32_16x16x32_bf16 v[0:3], v[4:7], v[36:39], v[0:3]
	ds_read_b128 v[4:7], v101 offset:17536
	s_waitcnt lgkmcnt(0)
	v_mfma_f32_16x16x32_bf16 v[0:3], v[4:7], v[32:35], v[0:3]
	ds_read_b128 v[4:7], v101 offset:17600
	s_waitcnt lgkmcnt(0)
	v_mfma_f32_16x16x32_bf16 v[8:11], v[4:7], v[12:15], v[0:3]
	s_nop 4
	v_add_f32_e64 v0, v88, v89
	v_add_f32_e64 v1, v89, v88
	s_nop 0
	v_mul_f32_e32 v2, v8, v8
	v_mul_f32_e32 v4, v9, v9
	v_mov_b32_e32 v1, v2
	v_pk_add_f32 v[2:3], v[90:91], v[90:91] op_sel:[0,1] op_sel_hi:[1,0]
	v_mul_f32_e32 v5, v10, v10
	v_mov_b32_e32 v3, v4
	v_pk_add_f32 v[0:1], v[0:1], v[2:3]
	v_mul_f32_e32 v2, v17, v17
	v_pk_fma_f32 v[2:3], v[16:17], v[16:17], v[2:3] op_sel_hi:[1,1,0]
	v_mul_f32_e32 v4, v19, v19
	v_mul_f32_e32 v6, v11, v11
	v_mov_b32_e32 v3, v5
	v_pk_fma_f32 v[4:5], v[18:19], v[18:19], v[4:5] op_sel_hi:[1,1,0]
	s_nop 0
	v_mov_b32_e32 v5, v6
	v_pk_add_f32 v[2:3], v[2:3], v[4:5]
	ds_read_b128 v[4:7], v101 offset:21760
	v_pk_add_f32 v[88:89], v[0:1], v[2:3]
	s_waitcnt vmcnt(18)
	s_waitcnt lgkmcnt(0)
	v_lshlrev_b32_e32 v0, 16, v154
	v_and_b32_e32 v1, 0xffff0000, v154
	v_lshlrev_b32_e32 v2, 16, v155
	v_and_b32_e32 v3, 0xffff0000, v155
	s_nop 1
	v_mfma_f32_16x16x32_bf16 v[0:3], v[4:7], v[40:43], v[0:3]
	ds_read_b128 v[4:7], v101 offset:21824
	s_waitcnt lgkmcnt(0)
	v_mfma_f32_16x16x32_bf16 v[0:3], v[4:7], v[36:39], v[0:3]
	ds_read_b128 v[4:7], v101 offset:21888
	s_waitcnt lgkmcnt(0)
	v_mfma_f32_16x16x32_bf16 v[0:3], v[4:7], v[32:35], v[0:3]
	ds_read_b128 v[4:7], v101 offset:21952
	s_waitcnt lgkmcnt(0)
	v_mfma_f32_16x16x32_bf16 v[4:7], v[4:7], v[12:15], v[0:3]
	s_nop 7
	v_pk_mul_f32 v[0:1], v[6:7], v[6:7]
	v_pk_mul_f32 v[2:3], v[4:5], v[4:5]
	s_nop 0
	v_pk_mov_b32 v[90:91], v[2:3], v[0:1] op_sel:[1,0]
	v_mov_b32_e32 v3, v1
	v_pk_add_f32 v[90:91], v[90:91], v[2:3]
	s_waitcnt vmcnt(17)
	s_waitcnt lgkmcnt(0)
	v_lshlrev_b32_e32 v0, 16, v156
	s_waitcnt vmcnt(16)
; __device__ __forceinline__ unsigned cvt_pk_bf16(float lo, float hi) { const f32x2cv v = {lo, hi}; const bf16x2cv b = __builtin_convertvector(v, bf16x2cv); return __builtin_bit_cast(unsigned, b); }
; #define LAS __attribute__((address_space(3)))
; __device__ __forceinline__ float bflo(unsigned w) { return __uint_as_float(w << 16); }
; __device__ __forceinline__ float bfhi(unsigned w) { return __uint_as_float(w & 0xffff0000u); }
; __device__ __forceinline__ f32x4 mma16(bf16x8_t x, bf16x8_t y, f32x4 c) { return __builtin_amdgcn_mfma_f32_16x16x32_bf16(x, y, c, 0, 0, 0); }
; __device__ __forceinline__ void hgrn_pass3_unit(Frame& F, const float* onw, int pu) {
;     ...
;     for (int vt = 0; vt < 8; ++vt) { const v2u oi = *(const v2u*)((const bf16*)F.out + (size_t)16 * 1024 * 1024 + row * 512 + h * 128 + 16 * vt + 4 * fq); f32x4 a; a[0] = bflo(oi.x); a[1] = bfhi(oi.x); a[2] = bflo(oi.y); a[3] = bfhi(oi.y);
; #pragma unroll
;         for (int kk = 0; kk < 4; ++kk) a = mma16(*(const LAS bf16x8_t*)(F.lds + cc * 34816 + (16 * vt + fr) * 272 + (8 * fq + 32 * kk) * 2), yq[kk], a);
;         o[vt] = a; ss += (a[0] * a[0] + a[1] * a[1]) + (a[2] * a[2] + a[3] * a[3]); }
;     ss += __shfl_xor(ss, 16); ss += __shfl_xor(ss, 32);
;     const float rs = __builtin_amdgcn_rsqf(ss * (1.f / 128.f) + EPS);
; #pragma unroll
;     for (int vt = 0; vt < 8; ++vt) { const int v0 = 16 * vt + 4 * fq; const f32x4 w4 = *(const f32x4*)(onw + v0); const v2u gt = *(const v2u*)(GH + row * 512 + h * 128 + v0);
;         v2u w; w.x = cvt_pk_bf16(o[vt][0] * rs * w4[0] * bflo(gt.x), o[vt][1] * rs * w4[1] * bfhi(gt.x)); w.y = cvt_pk_bf16(o[vt][2] * rs * w4[2] * bflo(gt.y), o[vt][3] * rs * w4[3] * bfhi(gt.y));
;         *(v2u*)(QO + row * DM + h * 128 + v0) = w; }
	v_and_b32_e32 v1, 0xffff0000, v156
	v_lshlrev_b32_e32 v2, 16, v157
	v_and_b32_e32 v3, 0xffff0000, v157
	s_nop 1
	v_mfma_f32_16x16x32_bf16 v[0:3], v[102:105], v[40:43], v[0:3]
	ds_read_b128 v[102:105], v101 offset:26176
	s_waitcnt lgkmcnt(0)
	v_mfma_f32_16x16x32_bf16 v[0:3], v[102:105], v[36:39], v[0:3]
	ds_read_b128 v[102:105], v101 offset:26240
	s_waitcnt lgkmcnt(0)
	v_mfma_f32_16x16x32_bf16 v[0:3], v[102:105], v[32:35], v[0:3]
	ds_read_b128 v[102:105], v101 offset:26304
	s_waitcnt lgkmcnt(0)
	v_mfma_f32_16x16x32_bf16 v[0:3], v[102:105], v[12:15], v[0:3]
	s_nop 0
	v_lshlrev_b32_e32 v102, 16, v158
	v_and_b32_e32 v103, 0xffff0000, v158
	v_lshlrev_b32_e32 v104, 16, v159
	v_and_b32_e32 v105, 0xffff0000, v159
	s_nop 1
	v_mfma_f32_16x16x32_bf16 v[40:43], v[106:109], v[40:43], v[102:105]
	s_nop 2
	ds_read_b128 v[102:105], v101 offset:30528
	s_waitcnt lgkmcnt(0)
	v_mfma_f32_16x16x32_bf16 v[36:39], v[102:105], v[36:39], v[40:43]
	s_nop 2
	ds_read_b128 v[40:43], v101 offset:30592
	s_waitcnt lgkmcnt(0)
	v_mfma_f32_16x16x32_bf16 v[32:35], v[40:43], v[32:35], v[36:39]
	s_nop 2
	ds_read_b128 v[36:39], v101 offset:30656
	s_waitcnt lgkmcnt(0)
	v_mfma_f32_16x16x32_bf16 v[12:15], v[36:39], v[12:15], v[32:35]
	s_nop 2
	v_add_f32_e64 v32, v88, v89
	v_add_f32_e64 v33, v89, v88
	s_nop 2
	v_mul_f32_e32 v34, v12, v12
	v_mul_f32_e32 v36, v13, v13
	v_mov_b32_e32 v33, v34
	v_pk_add_f32 v[34:35], v[90:91], v[90:91] op_sel:[0,1] op_sel_hi:[1,0]
	v_mul_f32_e32 v37, v14, v14
	v_mov_b32_e32 v35, v36
	v_pk_add_f32 v[32:33], v[32:33], v[34:35]
	v_mul_f32_e32 v34, v1, v1
	v_pk_fma_f32 v[34:35], v[0:1], v[0:1], v[34:35] op_sel_hi:[1,1,0]
	v_mul_f32_e32 v36, v3, v3
	v_mul_f32_e32 v38, v15, v15
	v_mov_b32_e32 v35, v37
	v_pk_fma_f32 v[36:37], v[2:3], v[2:3], v[36:37] op_sel_hi:[1,1,0]
	s_nop 0
	v_mov_b32_e32 v37, v38
	v_pk_add_f32 v[34:35], v[34:35], v[36:37]
	s_nop 0
	v_pk_add_f32 v[32:33], v[32:33], v[34:35]
	s_nop 0
	s_nop 0
	s_nop 0
	s_waitcnt vmcnt(7)
	v_add_f32_e32 v32, v32, v33
	ds_bpermute_b32 v33, v61, v32
	s_waitcnt lgkmcnt(0)
	v_add_f32_e32 v32, v32, v33
	ds_bpermute_b32 v33, v92, v32
	s_waitcnt lgkmcnt(0)
	v_add_f32_e32 v32, v32, v33
	v_fmamk_f32 v32, v32, 0x3c000000, v212
	v_rsq_f32_e32 v32, v32
	s_nop 0
	v_pk_mul_f32 v[28:29], v[28:29], v[32:33] op_sel_hi:[1,0]
	v_pk_mul_f32 v[24:25], v[24:25], v[32:33] op_sel_hi:[1,0]
	v_pk_mul_f32 v[26:27], v[26:27], v[32:33] op_sel_hi:[1,0]
	v_pk_mul_f32 v[20:21], v[20:21], v[32:33] op_sel_hi:[1,0]
	v_pk_mul_f32 v[22:23], v[22:23], v[32:33] op_sel_hi:[1,0]
	v_pk_mul_f32 v[16:17], v[16:17], v[32:33] op_sel_hi:[1,0]
	v_pk_mul_f32 v[18:19], v[18:19], v[32:33] op_sel_hi:[1,0]
	v_pk_mul_f32 v[8:9], v[8:9], v[32:33] op_sel_hi:[1,0]
	v_pk_mul_f32 v[10:11], v[10:11], v[32:33] op_sel_hi:[1,0]
	v_pk_mul_f32 v[4:5], v[4:5], v[32:33] op_sel_hi:[1,0]
	v_pk_mul_f32 v[6:7], v[6:7], v[32:33] op_sel_hi:[1,0]
	v_pk_mul_f32 v[0:1], v[0:1], v[32:33] op_sel_hi:[1,0]
	v_pk_mul_f32 v[2:3], v[2:3], v[32:33] op_sel_hi:[1,0]
	s_nop 0
	v_pk_mul_f32 v[28:29], v[160:161], v[28:29]
	v_lshlrev_b32_e32 v36, 16, v164
	v_and_b32_e32 v37, 0xffff0000, v164
	v_pk_mul_f32 v[28:29], v[28:29], v[36:37]
	s_nop 0
	v_cvt_pk_bf16_f32 v36, v28, v29
	v_pk_mul_f32 v[28:29], v[30:31], v[32:33] op_sel_hi:[1,0]
	v_lshlrev_b32_e32 v30, 16, v165
	v_pk_mul_f32 v[28:29], v[162:163], v[28:29]
	v_and_b32_e32 v31, 0xffff0000, v165
	v_pk_mul_f32 v[28:29], v[28:29], v[30:31]
	s_nop 0
	v_cvt_pk_bf16_f32 v37, v28, v29
	v_lshl_add_u64 v[28:29], v[82:83], 0, v[80:81]
	global_store_dwordx2 v[28:29], v[36:37], off
	s_nop 0
	s_nop 0
	s_waitcnt vmcnt(7)
; __device__ __forceinline__ unsigned cvt_pk_bf16(float lo, float hi) { const f32x2cv v = {lo, hi}; const bf16x2cv b = __builtin_convertvector(v, bf16x2cv); return __builtin_bit_cast(unsigned, b); }
; __device__ __forceinline__ float bflo(unsigned w) { return __uint_as_float(w << 16); }
; __device__ __forceinline__ float bfhi(unsigned w) { return __uint_as_float(w & 0xffff0000u); }
; __device__ __forceinline__ void hgrn_pass3_unit(Frame& F, const float* onw, int pu) {
;     ...
; #pragma unroll
;     for (int vt = 0; vt < 8; ++vt) { const int v0 = 16 * vt + 4 * fq; const f32x4 w4 = *(const f32x4*)(onw + v0); const v2u gt = *(const v2u*)(GH + row * 512 + h * 128 + v0);
;         v2u w; w.x = cvt_pk_bf16(o[vt][0] * rs * w4[0] * bflo(gt.x), o[vt][1] * rs * w4[1] * bfhi(gt.x)); w.y = cvt_pk_bf16(o[vt][2] * rs * w4[2] * bflo(gt.y), o[vt][3] * rs * w4[3] * bfhi(gt.y));
;         *(v2u*)(QO + row * DM + h * 128 + v0) = w; }
;     __syncthreads();
	s_nop 0
	v_pk_mul_f32 v[24:25], v[166:167], v[24:25]
	s_waitcnt lgkmcnt(0)
	v_lshlrev_b32_e32 v36, 16, v170
	v_and_b32_e32 v37, 0xffff0000, v170
	v_pk_mul_f32 v[26:27], v[168:169], v[26:27]
	v_lshlrev_b32_e32 v30, 16, v171
	v_and_b32_e32 v31, 0xffff0000, v171
	v_pk_mul_f32 v[24:25], v[24:25], v[36:37]
	v_pk_mul_f32 v[26:27], v[26:27], v[30:31]
	v_cvt_pk_bf16_f32 v24, v24, v25
	v_cvt_pk_bf16_f32 v25, v26, v27
	global_store_dwordx2 v[28:29], v[24:25], off offset:32
	s_nop 0
	s_nop 0
	s_waitcnt vmcnt(7)
	s_nop 0
	v_pk_mul_f32 v[20:21], v[20:21], v[172:173]
	s_waitcnt lgkmcnt(0)
	v_lshlrev_b32_e32 v24, 16, v176
	v_and_b32_e32 v25, 0xffff0000, v176
	v_pk_mul_f32 v[20:21], v[20:21], v[24:25]
	v_pk_mul_f32 v[22:23], v[22:23], v[174:175]
	v_lshlrev_b32_e32 v24, 16, v177
	v_and_b32_e32 v25, 0xffff0000, v177
	v_pk_mul_f32 v[22:23], v[22:23], v[24:25]
	v_cvt_pk_bf16_f32 v20, v20, v21
	v_cvt_pk_bf16_f32 v21, v22, v23
	global_store_dwordx2 v[28:29], v[20:21], off offset:64
	s_nop 0
	s_nop 0
	s_waitcnt vmcnt(7)
	s_nop 0
	v_pk_mul_f32 v[16:17], v[16:17], v[178:179]
	s_waitcnt lgkmcnt(0)
	v_lshlrev_b32_e32 v20, 16, v182
	v_and_b32_e32 v21, 0xffff0000, v182
	v_pk_mul_f32 v[16:17], v[16:17], v[20:21]
	v_pk_mul_f32 v[18:19], v[18:19], v[180:181]
	v_lshlrev_b32_e32 v20, 16, v183
	v_and_b32_e32 v21, 0xffff0000, v183
	v_pk_mul_f32 v[18:19], v[18:19], v[20:21]
	v_cvt_pk_bf16_f32 v16, v16, v17
	v_cvt_pk_bf16_f32 v17, v18, v19
	global_store_dwordx2 v[28:29], v[16:17], off offset:96
	s_nop 0
	s_nop 0
	s_waitcnt vmcnt(7)
	s_nop 0
	v_pk_mul_f32 v[8:9], v[8:9], v[184:185]
	s_waitcnt lgkmcnt(0)
	v_lshlrev_b32_e32 v16, 16, v188
	v_and_b32_e32 v17, 0xffff0000, v188
	v_pk_mul_f32 v[8:9], v[8:9], v[16:17]
	v_pk_mul_f32 v[10:11], v[10:11], v[186:187]
	v_lshlrev_b32_e32 v16, 16, v189
	v_and_b32_e32 v17, 0xffff0000, v189
	v_pk_mul_f32 v[10:11], v[10:11], v[16:17]
	v_cvt_pk_bf16_f32 v8, v8, v9
	v_cvt_pk_bf16_f32 v9, v10, v11
	global_store_dwordx2 v[28:29], v[8:9], off offset:128
	s_nop 0
	s_nop 0
	s_waitcnt vmcnt(7)
	s_nop 0
	v_pk_mul_f32 v[4:5], v[4:5], v[204:205]
	s_waitcnt lgkmcnt(0)
	v_lshlrev_b32_e32 v8, 16, v190
	v_and_b32_e32 v9, 0xffff0000, v190
	v_pk_mul_f32 v[4:5], v[4:5], v[8:9]
	v_pk_mul_f32 v[6:7], v[6:7], v[206:207]
	v_lshlrev_b32_e32 v8, 16, v191
	v_and_b32_e32 v9, 0xffff0000, v191
	v_pk_mul_f32 v[6:7], v[6:7], v[8:9]
	v_cvt_pk_bf16_f32 v4, v4, v5
	v_cvt_pk_bf16_f32 v5, v6, v7
	global_store_dwordx2 v[28:29], v[4:5], off offset:160
	s_nop 0
	s_nop 0
	s_waitcnt vmcnt(7)
	s_nop 0
	v_pk_mul_f32 v[0:1], v[0:1], v[208:209]
	s_waitcnt lgkmcnt(0)
	v_lshlrev_b32_e32 v4, 16, v218
	v_and_b32_e32 v5, 0xffff0000, v218
	v_pk_mul_f32 v[0:1], v[0:1], v[4:5]
	v_pk_mul_f32 v[2:3], v[2:3], v[210:211]
	v_lshlrev_b32_e32 v4, 16, v219
	v_and_b32_e32 v5, 0xffff0000, v219
	v_pk_mul_f32 v[2:3], v[2:3], v[4:5]
	v_cvt_pk_bf16_f32 v0, v0, v1
	v_cvt_pk_bf16_f32 v1, v2, v3
	global_store_dwordx2 v[28:29], v[0:1], off offset:192
	s_nop 0
	s_nop 0
	s_waitcnt vmcnt(7)
	v_pk_mul_f32 v[6:7], v[12:13], v[32:33] op_sel_hi:[1,0]
	s_nop 0
	v_pk_mul_f32 v[0:1], v[6:7], v[220:221]
	s_waitcnt lgkmcnt(0)
	v_lshlrev_b32_e32 v6, 16, v224
	v_and_b32_e32 v7, 0xffff0000, v224
	v_pk_mul_f32 v[0:1], v[0:1], v[6:7]
	v_pk_mul_f32 v[6:7], v[14:15], v[32:33] op_sel_hi:[1,0]
	v_lshlrev_b32_e32 v4, 16, v225
	v_pk_mul_f32 v[2:3], v[6:7], v[222:223]
	v_and_b32_e32 v5, 0xffff0000, v225
	v_pk_mul_f32 v[2:3], v[2:3], v[4:5]
	v_cvt_pk_bf16_f32 v0, v0, v1
	v_cvt_pk_bf16_f32 v1, v2, v3
	global_store_dwordx2 v[28:29], v[0:1], off offset:224
	s_waitcnt lgkmcnt(0)
	s_barrier
	s_cbranch_scc0 .LBB0_696
